# grid barrier: non-leader workgroups poll the cross-XCD release generation word directly instead of waiting for their XCD leader to republish it (one hop less per seam)
# speedup vs baseline: 1.0103x; 1.0103x over previous
.LBB0_61:
	s_or_b64 exec, exec, s[10:11]
	v_cvt_f32_u32_e32 v4, v2
	s_waitcnt vmcnt(0)
	v_readfirstlane_b32 s8, v3
	v_sub_u32_e32 v3, 0, v2
	v_rcp_iflag_f32_e32 v4, v4
	v_add_u32_e32 v5, s8, v1
	v_mul_f32_e32 v4, 0x4f7ffffe, v4
	v_cvt_u32_f32_e32 v4, v4
	v_mul_lo_u32 v1, v3, v4
	v_mul_hi_u32 v1, v4, v1
	v_add_u32_e32 v1, v4, v1
	v_mul_hi_u32 v1, v5, v1
	v_mul_lo_u32 v3, v1, v2
	v_sub_u32_e32 v3, v5, v3
	v_add_u32_e32 v4, 1, v1
	v_cmp_ge_u32_e32 vcc, v3, v2
	s_nop 1
	v_cndmask_b32_e32 v1, v1, v4, vcc
	v_sub_u32_e32 v4, v3, v2
	v_cndmask_b32_e32 v3, v3, v4, vcc
	v_add_u32_e32 v4, 1, v1
	v_cmp_ge_u32_e32 vcc, v3, v2
	v_add_u32_e32 v3, 1, v5
	s_nop 0
	v_cndmask_b32_e32 v1, v1, v4, vcc
	v_mul_lo_u32 v4, v2, v1
	v_add_u32_e32 v2, v4, v2
	v_cmp_ne_u32_e32 vcc, v3, v2
	s_and_saveexec_b64 s[8:9], vcc
	s_xor_b64 s[8:9], exec, s[8:9]
	s_cbranch_execz .LBB0_75
	s_waitcnt lgkmcnt(0)
	v_mov_b32_e32 v0, 0x7000
	global_load_dword v0, v0, s[76:77] offset:1280 sc1
	s_add_u32 s14, s76, 0x7500
	s_addc_u32 s15, s77, 0
	s_waitcnt vmcnt(0)
	v_cmp_eq_u32_e32 vcc, v0, v1
	s_and_saveexec_b64 s[10:11], vcc
	s_cbranch_execz .LBB0_74
	s_add_u32 s12, s76, 0x4200
	s_addc_u32 s13, s77, 0
	s_mov_b32 s26, 1
	s_mov_b64 s[16:17], 0
	v_mov_b32_e32 v0, 0
	s_branch .LBB0_65

.LBB0_181:
	s_or_b64 exec, exec, s[8:9]
	v_cvt_f32_u32_e32 v4, v2
	s_waitcnt vmcnt(0)
	v_readfirstlane_b32 s6, v3
	v_sub_u32_e32 v3, 0, v2
	v_rcp_iflag_f32_e32 v4, v4
	v_add_u32_e32 v5, s6, v1
	v_mul_f32_e32 v4, 0x4f7ffffe, v4
	v_cvt_u32_f32_e32 v4, v4
	v_mul_lo_u32 v1, v3, v4
	v_mul_hi_u32 v1, v4, v1
	v_add_u32_e32 v1, v4, v1
	v_mul_hi_u32 v1, v5, v1
	v_mul_lo_u32 v3, v1, v2
	v_sub_u32_e32 v3, v5, v3
	v_add_u32_e32 v4, 1, v1
	v_cmp_ge_u32_e32 vcc, v3, v2
	s_nop 1
	v_cndmask_b32_e32 v1, v1, v4, vcc
	v_sub_u32_e32 v4, v3, v2
	v_cndmask_b32_e32 v3, v3, v4, vcc
	v_add_u32_e32 v4, 1, v1
	v_cmp_ge_u32_e32 vcc, v3, v2
	v_add_u32_e32 v3, 1, v5
	s_nop 0
	v_cndmask_b32_e32 v1, v1, v4, vcc
	v_mul_lo_u32 v4, v2, v1
	v_add_u32_e32 v2, v4, v2
	v_cmp_ne_u32_e32 vcc, v3, v2
	s_and_saveexec_b64 s[6:7], vcc
	s_xor_b64 s[6:7], exec, s[6:7]
	s_cbranch_execz .LBB0_195
	s_waitcnt lgkmcnt(0)
	v_mov_b32_e32 v0, 0x7000
	global_load_dword v0, v0, s[76:77] offset:1280 sc1
	s_add_u32 s12, s76, 0x7500
	s_addc_u32 s13, s77, 0
	s_waitcnt vmcnt(0)
	v_cmp_eq_u32_e32 vcc, v0, v1
	s_and_saveexec_b64 s[8:9], vcc
	s_cbranch_execz .LBB0_194
	s_add_u32 s10, s76, 0x4200
	s_addc_u32 s11, s77, 0
	s_mov_b32 s24, 1
	s_mov_b64 s[14:15], 0
	v_mov_b32_e32 v0, 0
	s_branch .LBB0_185

.LBB0_422:
	s_or_b64 exec, exec, s[6:7]
	v_cvt_f32_u32_e32 v4, v2
	s_waitcnt vmcnt(0)
	v_readfirstlane_b32 s4, v3
	v_sub_u32_e32 v3, 0, v2
	v_rcp_iflag_f32_e32 v4, v4
	v_add_u32_e32 v5, s4, v1
	v_mul_f32_e32 v4, 0x4f7ffffe, v4
	v_cvt_u32_f32_e32 v4, v4
	v_mul_lo_u32 v1, v3, v4
	v_mul_hi_u32 v1, v4, v1
	v_add_u32_e32 v1, v4, v1
	v_mul_hi_u32 v1, v5, v1
	v_mul_lo_u32 v3, v1, v2
	v_sub_u32_e32 v3, v5, v3
	v_add_u32_e32 v4, 1, v1
	v_cmp_ge_u32_e32 vcc, v3, v2
	s_nop 1
	v_cndmask_b32_e32 v1, v1, v4, vcc
	v_sub_u32_e32 v4, v3, v2
	v_cndmask_b32_e32 v3, v3, v4, vcc
	v_add_u32_e32 v4, 1, v1
	v_cmp_ge_u32_e32 vcc, v3, v2
	v_add_u32_e32 v3, 1, v5
	s_nop 0
	v_cndmask_b32_e32 v1, v1, v4, vcc
	v_mul_lo_u32 v4, v2, v1
	v_add_u32_e32 v2, v4, v2
	v_cmp_ne_u32_e32 vcc, v3, v2
	s_and_saveexec_b64 s[4:5], vcc
	s_xor_b64 s[4:5], exec, s[4:5]
	s_cbranch_execz .LBB0_436
	s_waitcnt lgkmcnt(0)
	v_mov_b32_e32 v0, 0x7000
	global_load_dword v0, v0, s[76:77] offset:1280 sc1
	s_add_u32 s10, s76, 0x7500
	s_addc_u32 s11, s77, 0
	s_waitcnt vmcnt(0)
	v_cmp_eq_u32_e32 vcc, v0, v1
	s_and_saveexec_b64 s[6:7], vcc
	s_cbranch_execz .LBB0_435
	s_add_u32 s8, s76, 0x4200
	s_addc_u32 s9, s77, 0
	s_mov_b32 s22, 1
	s_mov_b64 s[12:13], 0
	v_mov_b32_e32 v0, 0
	s_branch .LBB0_426
